# wave role split in both attention units (MLA and GQA) + every hot MFMA loop placed inside one 4 KiB code page
# speedup vs baseline: 1.0058x; 1.0058x over previous
; #define ATT_SUMPACK(j) do { const float e0_ = (j) < 8 ? P0[2 * ((j) & 7)] : P1[2 * ((j) & 7)], e1_ = (j) < 8 ? P0[2 * ((j) & 7) + 1] : P1[2 * ((j) & 7) + 1]; \
;         if ((j) & 1) { rc += e0_; rd += e1_; } else { ra += e0_; rb += e1_; } S.pw[j] = cvtpk(e0_, e1_); } while (0)
; template <int GRP, bool has_next> __device__ __forceinline__ void att_step(const AttCtx<GRP>& C, AttState<GRP>& S, int s, f32x16& P0, f32x16& P1, f32x16& PN0, f32x16& PN1, u32x4& kreg, u32x4& preg, u32x4& vreg) {
;     ...
;     constexpr int NE = NKS - 1;
;     float ra = 0.f, rb = 0.f, rc = 0.f, rd = 0.f;
;     ...
; #pragma unroll
;     for (int c = 1; c < NKS; ++c) {
;         if (has_next) {
;             if (c == NK0) att_kfrag<GRP, NK0, NK1>(C, (s + 1) & 1, kfb);
;             const bf16x8 a0 = c < NK0 ? kfa[2 * c] : kfb[2 * (c - NK0)], a1 = c < NK0 ? kfa[2 * c + 1] : kfb[2 * (c - NK0) + 1];
;             PN0 = __builtin_amdgcn_mfma_f32_32x32x16_bf16(a0, S.qr[c], PN0, 0, 0, 0); PN1 = __builtin_amdgcn_mfma_f32_32x32x16_bf16(a1, S.qr[c], PN1, 0, 0, 0);
;         }
; #pragma unroll
;         for (int j = (c - 1) * 16 / NE; j < c * 16 / NE; ++j) {
;             if (j < 8) { P0[2 * j] = __builtin_amdgcn_exp2f(P0[2 * j]); P0[2 * j + 1] = __builtin_amdgcn_exp2f(P0[2 * j + 1]); }
;             else { P1[2 * (j - 8)] = __builtin_amdgcn_exp2f(P1[2 * (j - 8)]); P1[2 * (j - 8) + 1] = __builtin_amdgcn_exp2f(P1[2 * (j - 8) + 1]); }
;         }
;         if (c > 1) {
; #pragma unroll
;             for (int j = (c - 2) * 16 / NE; j < (c - 1) * 16 / NE; ++j) ATT_SUMPACK(j);
;         }
;         __builtin_amdgcn_sched_barrier(0);
;     }
;     if (has_next && S.refnz && t != 63) { PN0 = __builtin_amdgcn_mfma_f32_32x32x16_bf16(ones, qx, PN0, 0, 0, 0); PN1 = __builtin_amdgcn_mfma_f32_32x32x16_bf16(ones, qx, PN1, 0, 0, 0); }
.Lgqa_nomax1001:
	v_exp_f32_e32 v48, v48
	v_exp_f32_e32 v49, v49
	v_exp_f32_e32 v50, v50
	v_exp_f32_e32 v51, v51
	v_cvt_pk_bf16_f32 v216, v48, v49
	v_exp_f32_e32 v52, v52
	v_exp_f32_e32 v53, v53
	v_cvt_pk_bf16_f32 v217, v50, v51
	v_exp_f32_e32 v54, v54
	v_exp_f32_e32 v55, v55
	v_add_f32_e32 v248, v48, v52
	v_add_f32_e32 v249, v49, v53
	v_cvt_pk_bf16_f32 v218, v52, v53
	v_exp_f32_e32 v56, v56
	v_exp_f32_e32 v57, v57
	v_add_f32_e32 v250, v50, v54
	v_add_f32_e32 v251, v51, v55
	v_cvt_pk_bf16_f32 v219, v54, v55
	v_exp_f32_e32 v58, v58
	v_exp_f32_e32 v59, v59
	v_add_f32_e32 v248, v248, v56
	v_add_f32_e32 v249, v249, v57
	v_cvt_pk_bf16_f32 v220, v56, v57
	v_exp_f32_e32 v60, v60
	v_exp_f32_e32 v61, v61
	v_add_f32_e32 v250, v250, v58
	v_add_f32_e32 v251, v251, v59
	v_cvt_pk_bf16_f32 v221, v58, v59
	v_exp_f32_e32 v62, v62
	v_exp_f32_e32 v63, v63
	v_add_f32_e32 v248, v248, v60
	v_add_f32_e32 v249, v249, v61
	v_cvt_pk_bf16_f32 v222, v60, v61
	v_exp_f32_e32 v32, v32
	v_exp_f32_e32 v33, v33
	v_add_f32_e32 v250, v250, v62
	v_add_f32_e32 v251, v251, v63
	v_cvt_pk_bf16_f32 v223, v62, v63
	v_exp_f32_e32 v34, v34
	v_exp_f32_e32 v35, v35
	v_add_f32_e32 v248, v248, v32
	v_add_f32_e32 v249, v249, v33
	v_cvt_pk_bf16_f32 v224, v32, v33
	v_exp_f32_e32 v36, v36
	v_exp_f32_e32 v37, v37
	v_add_f32_e32 v250, v250, v34
	v_add_f32_e32 v251, v251, v35
	v_cvt_pk_bf16_f32 v225, v34, v35
	v_exp_f32_e32 v38, v38
	v_exp_f32_e32 v39, v39
	v_add_f32_e32 v248, v248, v36
	v_add_f32_e32 v249, v249, v37
	v_cvt_pk_bf16_f32 v226, v36, v37
	v_exp_f32_e32 v40, v40
	v_exp_f32_e32 v41, v41
	v_add_f32_e32 v250, v250, v38
	v_add_f32_e32 v251, v251, v39
	v_cvt_pk_bf16_f32 v227, v38, v39
	v_exp_f32_e32 v42, v42
	v_exp_f32_e32 v43, v43
	v_add_f32_e32 v248, v248, v40
	v_add_f32_e32 v249, v249, v41
	v_cvt_pk_bf16_f32 v228, v40, v41
	v_exp_f32_e32 v44, v44
	v_exp_f32_e32 v45, v45
	v_add_f32_e32 v250, v250, v42
	v_add_f32_e32 v251, v251, v43
	v_cvt_pk_bf16_f32 v229, v42, v43
	v_exp_f32_e32 v46, v46
	v_exp_f32_e32 v47, v47
	v_add_f32_e32 v248, v248, v44
	v_add_f32_e32 v249, v249, v45
	v_cvt_pk_bf16_f32 v230, v44, v45
	v_add_f32_e32 v250, v250, v46
	v_add_f32_e32 v251, v251, v47
	v_cvt_pk_bf16_f32 v231, v46, v47
	v_add_f32_e32 v248, v248, v249
	v_add_f32_e32 v250, v250, v251
	v_add_f32_e32 v248, v248, v250
	v_add_f32_e32 v148, v148, v248
	s_branch .Lpagefit_4
	s_nop 0
	s_nop 0
	s_nop 0
	s_nop 0
	s_nop 0
	s_nop 0
	s_nop 0
	s_nop 0
	s_nop 0
	s_nop 0
	s_nop 0
	s_nop 0
	s_nop 0
	s_nop 0
	s_nop 0
	s_nop 0
	s_nop 0
	s_nop 0
	s_nop 0
	s_nop 0
	s_nop 0
	s_nop 0
	s_nop 0
	s_nop 0
	s_nop 0
	s_nop 0
	s_nop 0
	s_nop 0
	s_nop 0
	s_nop 0
	s_nop 0
	s_nop 0
	s_nop 0
	s_nop 0
	s_nop 0
	s_nop 0
	s_nop 0
	s_nop 0
	s_nop 0
	s_nop 0
	s_nop 0
	s_nop 0
	s_nop 0
	s_nop 0
	s_nop 0
	s_nop 0
	s_nop 0
	s_nop 0
	s_nop 0
	s_nop 0
	s_nop 0
	s_nop 0
	s_nop 0
	s_nop 0
	s_nop 0
	s_nop 0
	s_nop 0
	s_nop 0
	s_nop 0
	s_nop 0
	s_nop 0
	s_nop 0
	s_nop 0
	s_nop 0
	s_nop 0
	s_nop 0
	s_nop 0
	s_nop 0
	s_nop 0
	s_nop 0
	s_nop 0
	s_nop 0
	s_nop 0
	s_nop 0
	s_nop 0
	s_nop 0
	s_nop 0
	s_nop 0
	s_nop 0
	s_nop 0
	s_nop 0
	s_nop 0
	s_nop 0
	s_nop 0
	s_nop 0
	s_nop 0
	s_nop 0
	s_nop 0
	s_nop 0
	s_nop 0
	s_nop 0
	s_nop 0
	s_nop 0
	s_nop 0
	s_nop 0
	s_nop 0
	s_nop 0
	s_nop 0
	s_nop 0
	s_nop 0
	s_nop 0
	s_nop 0
	s_nop 0
	s_nop 0
	s_nop 0
	s_nop 0
	s_nop 0
	s_nop 0
	s_nop 0
	s_nop 0
	s_nop 0
	s_nop 0
	s_nop 0
	s_nop 0
	s_nop 0
	s_nop 0
	s_nop 0
	s_nop 0
	s_nop 0
	s_nop 0
	s_nop 0
	s_nop 0
	s_nop 0
	s_nop 0
	s_nop 0
	s_nop 0
	s_nop 0
	s_nop 0
	s_nop 0
	s_nop 0
	s_nop 0
	s_nop 0
	s_nop 0
	s_nop 0
	s_nop 0
	s_nop 0
	s_nop 0
	s_nop 0
	s_nop 0
	s_nop 0
	s_nop 0
	s_nop 0
	s_nop 0
	s_nop 0
	s_nop 0
	s_nop 0
	s_nop 0
	s_nop 0
	s_nop 0
	s_nop 0
	s_nop 0
	s_nop 0
	s_nop 0
	s_nop 0
	s_nop 0
	s_nop 0
	s_nop 0
	s_nop 0
	s_nop 0
	s_nop 0
	s_nop 0
	s_nop 0
	s_nop 0
	s_nop 0
	s_nop 0
	s_nop 0
	s_nop 0
	s_nop 0
	s_nop 0
	s_nop 0
.Lpagefit_4:
.Lgqa_L_loop:
	ds_read_b128 v[156:159], v149 offset:13312
	ds_read_b128 v[160:163], v149 offset:19968
	ds_read_b128 v[164:167], v149 offset:13344
	ds_read_b128 v[168:171], v149 offset:20000
	ds_read_b128 v[172:175], v149 offset:13376
	ds_read_b128 v[176:179], v149 offset:20032
	s_waitcnt lgkmcnt(5)
	v_mfma_f32_32x32x16_bf16 v[80:95], v[156:159], v[112:115], 0
	ds_read_b128 v[156:159], v149 offset:13408
	s_waitcnt lgkmcnt(5)
	v_mfma_f32_32x32x16_bf16 v[64:79], v[160:163], v[112:115], 0
	ds_read_b128 v[160:163], v149 offset:20064
	s_waitcnt lgkmcnt(5)
	v_mfma_f32_32x32x16_bf16 v[80:95], v[164:167], v[108:111], v[80:95]
	ds_read_b128 v[232:235], v146 offset:26624
	s_waitcnt lgkmcnt(5)
	v_mfma_f32_32x32x16_bf16 v[64:79], v[168:171], v[108:111], v[64:79]
	ds_read_b128 v[236:239], v146 offset:31232
	s_waitcnt lgkmcnt(5)
	v_mfma_f32_32x32x16_bf16 v[80:95], v[172:175], v[104:107], v[80:95]
	ds_read_b128 v[240:243], v146 offset:26656
	s_waitcnt lgkmcnt(5)
	v_mfma_f32_32x32x16_bf16 v[64:79], v[176:179], v[104:107], v[64:79]
	ds_read_b128 v[244:247], v146 offset:31264
	s_waitcnt lgkmcnt(5)
	v_mfma_f32_32x32x16_bf16 v[80:95], v[156:159], v[100:103], v[80:95]
	s_waitcnt lgkmcnt(4)
	v_mfma_f32_32x32x16_bf16 v[64:79], v[160:163], v[100:103], v[64:79]
	s_cmp_eq_u32 s62, 0
	s_cbranch_scc1 .Lgqa_nrz1003
	v_xor_b32_e32 v195, 0x80000000, v152
	s_mov_b32 s18, s16
	s_mov_b32 s19, s16
	s_mov_b32 s17, s16
	v_mov_b64_e32 v[182:183], s[18:19]
	v_mov_b64_e32 v[180:181], s[16:17]
	s_mov_b64 vcc, s[0:1]
	v_cndmask_b32_sdwa v96, v97, v195, vcc dst_sel:DWORD dst_unused:UNUSED_PAD src0_sel:DWORD src1_sel:WORD_1
	v_mov_b32_e32 v98, v97
	v_mov_b32_e32 v99, v97
	s_nop 1
	v_mfma_f32_32x32x16_bf16 v[80:95], v[180:183], v[96:99], v[80:95]
	v_mfma_f32_32x32x16_bf16 v[64:79], v[180:183], v[96:99], v[64:79]

; template <int GRP> ...
;     ...
;     if (wid >= 4) __builtin_amdgcn_s_setprio(1);
;     asm volatile("s_nop 15\n\ts_nop 7" : "+v"(pa0), "+v"(pa1));
;     for (int s = 0; s < NSTEP - 2; s += 2) { att_step<GRP, true>(C, S, s, pa0, pa1, pb0, pb1, kA, pA, vA); att_step<GRP, true>(C, S, s + 1, pb0, pb1, pa0, pa1, kA, pA, vA); }
;     att_step<GRP, true>(C, S, NSTEP - 2, pa0, pa1, pb0, pb1, kA, pA, vA); att_step<GRP, false>(C, S, NSTEP - 1, pb0, pb1, pa0, pa1, kA, pA, vA);
.Lgqa_T_entry:
	s_setprio 1
	s_branch .Lpagefit_5
	s_nop 0
	s_nop 0
	s_nop 0
	s_nop 0
	s_nop 0
	s_nop 0
	s_nop 0
	s_nop 0
	s_nop 0
	s_nop 0
	s_nop 0
	s_nop 0
	s_nop 0
	s_nop 0
	s_nop 0
	s_nop 0
	s_nop 0
	s_nop 0
	s_nop 0
	s_nop 0
	s_nop 0
	s_nop 0
	s_nop 0
	s_nop 0
	s_nop 0
	s_nop 0
	s_nop 0
	s_nop 0
	s_nop 0
	s_nop 0
	s_nop 0
	s_nop 0
	s_nop 0
	s_nop 0
	s_nop 0
	s_nop 0
	s_nop 0
	s_nop 0
	s_nop 0
	s_nop 0
	s_nop 0
	s_nop 0
	s_nop 0
	s_nop 0
	s_nop 0
	s_nop 0
	s_nop 0
	s_nop 0
	s_nop 0
	s_nop 0
	s_nop 0
	s_nop 0
	s_nop 0
	s_nop 0
	s_nop 0
	s_nop 0
	s_nop 0
	s_nop 0
	s_nop 0
	s_nop 0
	s_nop 0
	s_nop 0
	s_nop 0
	s_nop 0
	s_nop 0
	s_nop 0
	s_nop 0
	s_nop 0
	s_nop 0
	s_nop 0
	s_nop 0
	s_nop 0
	s_nop 0
	s_nop 0
	s_nop 0
	s_nop 0
	s_nop 0
	s_nop 0
	s_nop 0
	s_nop 0
	s_nop 0
	s_nop 0
	s_nop 0
	s_nop 0
	s_nop 0
	s_nop 0
	s_nop 0
	s_nop 0
	s_nop 0
	s_nop 0
	s_nop 0
	s_nop 0
	s_nop 0
	s_nop 0
	s_nop 0
	s_nop 0
	s_nop 0
	s_nop 0
	s_nop 0
	s_nop 0
	s_nop 0
	s_nop 0
	s_nop 0
	s_nop 0
	s_nop 0
	s_nop 0
	s_nop 0
	s_nop 0
	s_nop 0
	s_nop 0
	s_nop 0
	s_nop 0
	s_nop 0
	s_nop 0
	s_nop 0
	s_nop 0
	s_nop 0
	s_nop 0
	s_nop 0
	s_nop 0
	s_nop 0
	s_nop 0
	s_nop 0
	s_nop 0
	s_nop 0
	s_nop 0
	s_nop 0
	s_nop 0
	s_nop 0
	s_nop 0
	s_nop 0
	s_nop 0
	s_nop 0
	s_nop 0
	s_nop 0
	s_nop 0
	s_nop 0
	s_nop 0
	s_nop 0
	s_nop 0
	s_nop 0
	s_nop 0
	s_nop 0
	s_nop 0
	s_nop 0
	s_nop 0
	s_nop 0
	s_nop 0
	s_nop 0
	s_nop 0
	s_nop 0
	s_nop 0
	s_nop 0
	s_nop 0
	s_nop 0
	s_nop 0
	s_nop 0
	s_nop 0
	s_nop 0
	s_nop 0
	s_nop 0
	s_nop 0
	s_nop 0
	s_nop 0
	s_nop 0
	s_nop 0
	s_nop 0
	s_nop 0
	s_nop 0
	s_nop 0
	s_nop 0
	s_nop 0
	s_nop 0
	s_nop 0
	s_nop 0
	s_nop 0
	s_nop 0
	s_nop 0
	s_nop 0
	s_nop 0
	s_nop 0
	s_nop 0
	s_nop 0
	s_nop 0
	s_nop 0
	s_nop 0
	s_nop 0
	s_nop 0
	s_nop 0
	s_nop 0
	s_nop 0
	s_nop 0
	s_nop 0
	s_nop 0
	s_nop 0
	s_nop 0
	s_nop 0
	s_nop 0
	s_nop 0
	s_nop 0
	s_nop 0
	s_nop 0
	s_nop 0
	s_nop 0
	s_nop 0
	s_nop 0
	s_nop 0
	s_nop 0
	s_nop 0
	s_nop 0
	s_nop 0
	s_nop 0
	s_nop 0
	s_nop 0
	s_nop 0
	s_nop 0
	s_nop 0
	s_nop 0
	s_nop 0
	s_nop 0
	s_nop 0
	s_nop 0
	s_nop 0
	s_nop 0
	s_nop 0
	s_nop 0
	s_nop 0
	s_nop 0
	s_nop 0
	s_nop 0
	s_nop 0
	s_nop 0
	s_nop 0
	s_nop 0
	s_nop 0
	s_nop 0
	s_nop 0
	s_nop 0
	s_nop 0
	s_nop 0
	s_nop 0
	s_nop 0
	s_nop 0
	s_nop 0
	s_nop 0
	s_nop 0
	s_nop 0
	s_nop 0
	s_nop 0
	s_nop 0
	s_nop 0
	s_nop 0
	s_nop 0
	s_nop 0
	s_nop 0
	s_nop 0
	s_nop 0
	s_nop 0
	s_nop 0
	s_nop 0
	s_nop 0
	s_nop 0
	s_nop 0
	s_nop 0
	s_nop 0
	s_nop 0
	s_nop 0
	s_nop 0
	s_nop 0
	s_nop 0
	s_nop 0
	s_nop 0
	s_nop 0
	s_nop 0
	s_nop 0
	s_nop 0
	s_nop 0
	s_nop 0
	s_nop 0
	s_nop 0
	s_nop 0
	s_nop 0
	s_nop 0
	s_nop 0
	s_nop 0
	s_nop 0
	s_nop 0
	s_nop 0
	s_nop 0
	s_nop 0
	s_nop 0
	s_nop 0
	s_nop 0
	s_nop 0
	s_nop 0
	s_nop 0
	s_nop 0
	s_nop 0
	s_nop 0
	s_nop 0
	s_nop 0
	s_nop 0
	s_nop 0
	s_nop 0
	s_nop 0
	s_nop 0
	s_nop 0
	s_nop 0
	s_nop 0
	s_nop 0
	s_nop 0
	s_nop 0
	s_nop 0
	s_nop 0
	s_nop 0
	s_nop 0
	s_nop 0
	s_nop 0
	s_nop 0
	s_nop 0
	s_nop 0
	s_nop 0
	s_nop 0
	s_nop 0
	s_nop 0
	s_nop 0
	s_nop 0
	s_nop 0
	s_nop 0
	s_nop 0
	s_nop 0
	s_nop 0
	s_nop 0
	s_nop 0
	s_nop 0
	s_nop 0
	s_nop 0
	s_nop 0
	s_nop 0
	s_nop 0
	s_nop 0
	s_nop 0
	s_nop 0
	s_nop 0
	s_nop 0
	s_nop 0
	s_nop 0
	s_nop 0
	s_nop 0
	s_nop 0
	s_nop 0
	s_nop 0
	s_nop 0
	s_nop 0
	s_nop 0
	s_nop 0
	s_nop 0
	s_nop 0
	s_nop 0
	s_nop 0
	s_nop 0
	s_nop 0
	s_nop 0
	s_nop 0
	s_nop 0
	s_nop 0
	s_nop 0
	s_nop 0
	s_nop 0
	s_nop 0
	s_nop 0
	s_nop 0
	s_nop 0
	s_nop 0
	s_nop 0
	s_nop 0
	s_nop 0
	s_nop 0
	s_nop 0
	s_nop 0
	s_nop 0
	s_nop 0
	s_nop 0
	s_nop 0
	s_nop 0
	s_nop 0
	s_nop 0
	s_nop 0
	s_nop 0
	s_nop 0
	s_nop 0
	s_nop 0
	s_nop 0
	s_nop 0
	s_nop 0
	s_nop 0
	s_nop 0
	s_nop 0
	s_nop 0
	s_nop 0
	s_nop 0
	s_nop 0
	s_nop 0
	s_nop 0
	s_nop 0
	s_nop 0
	s_nop 0
	s_nop 0
	s_nop 0
	s_nop 0
	s_nop 0
	s_nop 0
	s_nop 0
	s_nop 0
	s_nop 0
	s_nop 0
	s_nop 0
	s_nop 0
	s_nop 0
	s_nop 0
	s_nop 0
	s_nop 0
	s_nop 0
	s_nop 0
	s_nop 0
	s_nop 0
	s_nop 0
	s_nop 0
	s_nop 0
	s_nop 0
	s_nop 0
	s_nop 0
	s_nop 0
	s_nop 0
	s_nop 0
	s_nop 0
	s_nop 0
	s_nop 0
	s_nop 0
	s_nop 0
	s_nop 0
	s_nop 0
	s_nop 0
	s_nop 0
	s_nop 0
	s_nop 0
	s_nop 0
	s_nop 0
	s_nop 0
	s_nop 0
	s_nop 0
	s_nop 0
	s_nop 0
	s_nop 0
	s_nop 0
	s_nop 0
	s_nop 0
	s_nop 0
	s_nop 0
	s_nop 0
	s_nop 0
	s_nop 0
	s_nop 0
	s_nop 0
	s_nop 0
	s_nop 0
	s_nop 0
	s_nop 0
	s_nop 0
	s_nop 0
	s_nop 0
	s_nop 0
	s_nop 0
	s_nop 0
	s_nop 0
	s_nop 0
	s_nop 0
	s_nop 0
	s_nop 0
	s_nop 0
	s_nop 0
	s_nop 0
	s_nop 0
	s_nop 0
	s_nop 0
	s_nop 0
	s_nop 0
	s_nop 0
	s_nop 0
	s_nop 0
	s_nop 0
	s_nop 0
	s_nop 0
	s_nop 0
	s_nop 0
	s_nop 0
	s_nop 0
	s_nop 0
	s_nop 0
	s_nop 0
	s_nop 0
	s_nop 0
	s_nop 0
	s_nop 0
	s_nop 0
	s_nop 0
	s_nop 0
	s_nop 0
	s_nop 0
	s_nop 0
	s_nop 0
	s_nop 0
	s_nop 0
	s_nop 0
	s_nop 0
	s_nop 0
	s_nop 0
	s_nop 0
	s_nop 0
	s_nop 0
	s_nop 0
	s_nop 0
	s_nop 0
	s_nop 0
	s_nop 0
	s_nop 0
	s_nop 0
	s_nop 0
	s_nop 0
	s_nop 0
	s_nop 0
	s_nop 0
	s_nop 0
	s_nop 0
	s_nop 0
	s_nop 0
	s_nop 0
	s_nop 0
	s_nop 0
	s_nop 0
	s_nop 0
	s_nop 0
	s_nop 0
	s_nop 0
	s_nop 0
	s_nop 0
	s_nop 0
	s_nop 0
	s_nop 0
	s_nop 0
	s_nop 0
	s_nop 0
	s_nop 0
	s_nop 0
	s_nop 0
	s_nop 0
	s_nop 0
	s_nop 0
	s_nop 0
	s_nop 0
	s_nop 0
	s_nop 0
	s_nop 0
	s_nop 0
	s_nop 0
	s_nop 0
	s_nop 0
	s_nop 0
	s_nop 0
	s_nop 0
	s_nop 0
	s_nop 0
	s_nop 0
	s_nop 0
	s_nop 0
	s_nop 0
	s_nop 0
	s_nop 0
	s_nop 0
	s_nop 0
	s_nop 0
	s_nop 0
	s_nop 0
	s_nop 0
	s_nop 0
	s_nop 0
	s_nop 0
	s_nop 0
	s_nop 0
	s_nop 0
	s_nop 0
	s_nop 0
	s_nop 0
	s_nop 0
	s_nop 0
	s_nop 0
	s_nop 0
	s_nop 0
	s_nop 0
	s_nop 0
	s_nop 0
	s_nop 0
	s_nop 0
	s_nop 0
	s_nop 0
	s_nop 0
	s_nop 0
	s_nop 0
	s_nop 0
	s_nop 0
	s_nop 0
	s_nop 0
	s_nop 0
	s_nop 0
	s_nop 0
	s_nop 0
	s_nop 0
	s_nop 0
	s_nop 0
	s_nop 0
	s_nop 0
	s_nop 0
	s_nop 0
	s_nop 0
	s_nop 0
	s_nop 0
	s_nop 0
	s_nop 0
	s_nop 0
	s_nop 0
	s_nop 0
	s_nop 0
	s_nop 0
	s_nop 0
	s_nop 0
	s_nop 0
	s_nop 0
	s_nop 0
	s_nop 0
	s_nop 0
	s_nop 0
	s_nop 0
	s_nop 0
	s_nop 0
	s_nop 0
	s_nop 0
	s_nop 0
	s_nop 0
	s_nop 0
	s_nop 0
	s_nop 0
	s_nop 0
	s_nop 0
	s_nop 0
	s_nop 0
	s_nop 0
	s_nop 0
	s_nop 0
	s_nop 0
	s_nop 0
	s_nop 0
	s_nop 0
	s_nop 0
	s_nop 0
	s_nop 0
	s_nop 0
	s_nop 0
	s_nop 0
	s_nop 0
	s_nop 0
	s_nop 0
	s_nop 0
	s_nop 0
	s_nop 0
	s_nop 0
	s_nop 0
	s_nop 0
	s_nop 0
	s_nop 0
	s_nop 0
	s_nop 0
	s_nop 0
	s_nop 0
	s_nop 0
	s_nop 0
	s_nop 0
	s_nop 0
	s_nop 0
	s_nop 0
	s_nop 0
	s_nop 0
	s_nop 0
	s_nop 0
	s_nop 0
	s_nop 0
	s_nop 0
	s_nop 0
	s_nop 0
	s_nop 0
	s_nop 0
	s_nop 0
	s_nop 0
	s_nop 0
	s_nop 0
	s_nop 0
	s_nop 0
	s_nop 0
	s_nop 0
	s_nop 0
; #define LAS __attribute__((address_space(3)))
; __device__ __forceinline__ float xhalf_max(float m) { auto rr = __builtin_amdgcn_permlane32_swap(__float_as_uint(m), __float_as_uint(m), false, false); return fmaxf(__uint_as_float(rr[0]), __uint_as_float(rr[1])); }
; __device__ __forceinline__ float max3f(float a, float b, float c) { float r; asm("v_max3_f32 %0, %1, %2, %3" : "=v"(r) : "v"(a), "v"(b), "v"(c)); return r; }
; template <int GRP> __device__ __forceinline__ void att_ldk(const AttCtx<GRP>& C, int step, u32x4& kreg, u32x4& preg) {
;     const int h = C.h0 + (step >> 6), t = step & 63, kvh = GRP == 0 ? h : (h >> 2);
;     kreg = *(const u32x4*)(C.kl + (kvh * 64 + t) * 4096);
;     if (GRP == 0 && C.tid < 256) preg = *(const u32x4*)(C.pl + t * 2048);
; }
; template <int GRP> __device__ __forceinline__ void att_stk(const AttCtx<GRP>& C, int buf, const u32x4& kreg, const u32x4& preg) {
;     *(LAS u32x4*)(C.lds + buf * KBUF + C.kwo) = kreg; if (GRP == 0 && C.tid < 256) *(LAS u32x4*)(C.lds + buf * KBUF + C.pwo) = preg;
; }
; template <int GRP> __device__ __forceinline__ void att_stld(const AttCtx<GRP>& C, int s, u32x4& kreg, u32x4& preg, u32x4& vreg) {
;     constexpr int NSTEP = 256;
;     if (s + 2 < NSTEP) att_stk<GRP>(C, s & 1, kreg, preg);
;     if (s + 1 < NSTEP) att_stv<GRP>(C, (s + 1) & 1, vreg);
;     if (s + 3 < NSTEP) att_ldk<GRP>(C, s + 3, kreg, preg);
;     if (s + 2 < NSTEP) att_ldv<GRP>(C, s + 2, vreg);
; template <int GRP, bool has_next> __device__ __forceinline__ void att_step(const AttCtx<GRP>& C, AttState<GRP>& S, int s, f32x16& P0, f32x16& P1, f32x16& PN0, f32x16& PN1, u32x4& kreg, u32x4& preg, u32x4& vreg) {
;     ...
;     if ((t & 7) == 0) {
;         float ma = max3f(P0[0], P0[1], P0[2]), mb = max3f(P0[3], P0[4], P0[5]), mc = max3f(P1[0], P1[1], P1[2]), md = max3f(P1[3], P1[4], P1[5]);
;         ma = max3f(ma, P0[6], P0[7]); mb = max3f(mb, P0[8], P0[9]); mc = max3f(mc, P1[6], P1[7]); md = max3f(md, P1[8], P1[9]);
;         ma = max3f(ma, P0[10], P0[11]); mb = max3f(mb, P0[12], P0[13]); mc = max3f(mc, P1[10], P1[11]); md = max3f(md, P1[12], P1[13]);
;         ma = max3f(ma, P0[14], P0[15]); mc = max3f(mc, P1[14], P1[15]); ma = max3f(ma, mb, mc); mb = md;
;         const float mx = xhalf_max(max2f(ma, mb));
;         const int up = __any(mx > THR), dn = (t == 0) ? __any(mx < -THR) : 0;
.Lpagefit_5:
.LBB0_808:
	s_add_i32 s88, s61, 3
	s_lshr_b32 s89, s88, 6
	s_add_i32 s89, s89, s60
	s_lshl_b32 s89, s89, 4
	s_and_b32 s89, s89, 0xffffffc0
	s_and_b32 s88, s88, 63
	s_or_b32 s88, s89, s88
	s_lshl_b32 s88, s88, 12
	s_ashr_i32 s89, s88, 31
	s_add_i32 s84, s61, 2
	s_lshr_b32 s85, s84, 6
	s_add_i32 s85, s85, s60
	s_lshl_b32 s85, s85, 4
	s_and_b32 s85, s85, 0xffffffc0
	s_and_b32 s84, s84, 63
	s_or_b32 s84, s85, s84
	s_lshl_b32 s84, s84, 12
	s_ashr_i32 s85, s84, 31
	s_waitcnt vmcnt(1)
	ds_write_b128 v150, v[116:119]
	v_lshl_add_u64 v[192:193], s[88:89], 1, v[140:141]
	s_waitcnt vmcnt(0)
	ds_write_b128 v147, v[120:123] offset:35840
	v_lshl_add_u64 v[190:191], s[84:85], 1, v[138:139]
	global_load_dwordx4 v[116:119], v[192:193], off
	global_load_dwordx4 v[124:127], v[190:191], off
	s_and_b32 s10, s61, 6
	s_cmp_lg_u32 s10, 0
	s_cbranch_scc1 .Lgqa_nomax1012
	v_max3_f32 v96, v48, v49, v50
	v_max3_f32 v99, v32, v33, v34
	v_max3_f32 v98, v51, v52, v53
	v_max3_f32 v153, v35, v36, v37
	s_and_b32 s10, s61, 56
	v_max3_f32 v96, v96, v54, v55
	v_max3_f32 v99, v99, v38, v39
	v_max3_f32 v98, v98, v56, v57
	v_max3_f32 v153, v153, v40, v41
	s_cmp_eq_u32 s10, 0
	v_max3_f32 v96, v96, v58, v59
	v_max3_f32 v99, v99, v42, v43
	v_max3_f32 v98, v98, v60, v61
	v_max3_f32 v153, v153, v44, v45
	s_cselect_b64 s[6:7], -1, 0
	v_max3_f32 v96, v96, v62, v63
	v_max3_f32 v99, v99, v46, v47
	s_cmp_lg_u32 s10, 0
	v_max3_f32 v96, v96, v98, v99
	s_nop 0
	v_max_f32_e32 v96, v96, v153
	s_nop 0
	v_mov_b32_e32 v98, v96
	s_nop 1
	v_permlane32_swap_b32_e32 v96, v98
	v_max_f32_e32 v98, v98, v98
	v_max_f32_e32 v96, v96, v96
	v_max_f32_e32 v96, v96, v98
	v_cmp_lt_f32_e32 vcc, s54, v96
	v_mov_b32_e32 v98, 0
	s_cbranch_scc1 .Lgqa_mx1013
	v_cmp_gt_f32_e64 s[10:11], s55, v96
	s_cmp_lg_u64 s[10:11], 0
	s_cselect_b64 s[10:11], -1, 0
	v_cndmask_b32_e64 v98, 0, 1, s[10:11]

; #define PG8_WAIT_V(n) asm volatile("s_waitcnt vmcnt(" #n ")" ::: "memory")
; #define PG8_BAR __builtin_amdgcn_s_barrier()
; template <class Epi, class Sched, bool ALIGN_EPI = false, bool SP2 = false>
; __device__ __forceinline__ void gemm_phase(PG8_LAS unsigned char* lds, const Gemm g, const Sched S, const Epi E) {
;     ...
; #pragma unroll
;     for (int a = 0; a < 2; ++a)
; #pragma unroll
;         for (int b = 0; b < 2; ++b)
; #pragma unroll
;             for (int m = 0; m < 4; ++m)
; #pragma unroll
;                 for (int n = 0; n < 2; ++n) acc[a][b][m][n] = (f32x4){0.f, 0.f, 0.f, 0.f};
;     ...
;     const char* cA = (const char*)g.A + (size_t)cur.pm * tstep; const char* cB = (const char*)g.Bt + (size_t)cur.pn * tstep;
;     S.a_ready(cur);
;     if constexpr (SP2) {
;         PG8_STAGE(PG8_SB(0, 0), cB, voffB); PG8_STAGE(PG8_SB(0, 1), cB + hstep, voffB); PG8_STAGE(PG8_SA(0, 0), cA, voffA); PG8_STAGE(PG8_SA(0, 1), cA + hstep, voffA);
;         if (wr == 1) PG8_BAR;
;         PG8_WAIT_V(2); PG8_BAR;
;         PG8_STAGE(PG8_SB(1, 0), cB + kstep, voffB); PG8_STAGE(PG8_SA(1, 0), cA + kstep, voffA); PG8_STAGE(PG8_SB(1, 1), cB + hstep + kstep, voffB);
;         PG8_WAIT_V(6); PG8_BAR;
;     } else {
;         PG8_STAGE(PG8_SB(0, 0), cB, voffB); PG8_STAGE(PG8_SA(0, 0), cA, voffA); PG8_STAGE(PG8_SB(0, 1), cB + hstep, voffB); PG8_STAGE(PG8_SA(0, 1), cA + hstep, voffA);
;         if (wr == 1) PG8_BAR;
;         PG8_WAIT_V(4); PG8_BAR;
;         PG8_STAGE(PG8_SB(1, 0), cB + kstep, voffB); PG8_STAGE(PG8_SA(1, 0), cA + kstep, voffA); PG8_STAGE(PG8_SB(1, 1), cB + hstep + kstep, voffB);
;         PG8_WAIT_V(6); PG8_BAR;
;     }
;     for (;;) {
;         const bool has_next = S.next(ui + 1, nxt);
;         const char* nA = has_next ? (const char*)g.A + (size_t)nxt.pm * tstep : cA; const char* nB = has_next ? (const char*)g.Bt + (size_t)nxt.pn * tstep : cB;
;         for (int t = 0; t < nt; t += 2) {
;             if constexpr (Epi::MIDT >= 0) { if (t == Epi::MIDT) E.mid(acc, cur, wr, fr); }
;             const bool last = (t == nt - 2);
;             const char* a1 = cA + (size_t)(t + 1) * kstep;
;             const char* a2 = last ? nA : cA + (size_t)(t + 2) * kstep; const char* b2 = last ? nB : cB + (size_t)(t + 2) * kstep;
;             const char* a3 = a2 + kstep; const char* b3 = b2 + kstep;
.LBB0_897:
	s_ashr_i32 s51, s50, 31
	s_lshl_b64 s[10:11], s[50:51], 19
	s_add_u32 s52, s48, s10
	v_lshl_add_u32 v2, s64, 10, v171
	s_addc_u32 s53, s49, s11
	v_add_u32_e32 v4, 0x200, v2
	s_and_b64 s[10:11], s[0:1], exec
	v_ashrrev_i32_e32 v5, 31, v4
	s_cselect_b32 s51, s53, s67
	s_cselect_b32 s72, s52, s66
	s_ashr_i32 s45, s44, 31
	v_lshl_add_u64 v[130:131], v[4:5], 2, s[46:47]
	v_add_u32_e32 v4, 0x240, v2
	s_lshl_b64 s[10:11], s[44:45], 19
	v_readlane_b32 s14, v255, 34
	v_ashrrev_i32_e32 v3, 31, v2
	v_ashrrev_i32_e32 v5, 31, v4
	v_readlane_b32 s15, v255, 35
	s_add_u32 s62, s14, s10
	v_lshl_add_u64 v[128:129], v[2:3], 2, s[46:47]
	v_lshl_add_u64 v[132:133], v[4:5], 2, s[46:47]
	v_add_u32_e32 v4, 0x280, v2
	v_add_u32_e32 v2, 0x2c0, v2
	s_addc_u32 s63, s15, s11
	v_ashrrev_i32_e32 v3, 31, v2
	s_and_b64 s[10:11], s[0:1], exec
	v_ashrrev_i32_e32 v5, 31, v4
	v_lshl_add_u64 v[136:137], v[2:3], 2, s[46:47]
	v_mov_b32_e32 v2, v0
	v_mov_b32_e32 v3, v0
	s_cselect_b32 s45, s63, s7
	s_cselect_b32 s73, s62, s6
	v_lshl_add_u64 v[134:135], v[4:5], 2, s[46:47]
	s_add_u32 s74, s6, 0x100
	v_mov_b32_e32 v1, v0
	v_mov_b64_e32 v[6:7], v[2:3]
	v_mov_b64_e32 v[10:11], v[2:3]
	v_mov_b64_e32 v[22:23], v[2:3]
	v_mov_b64_e32 v[26:27], v[2:3]
	v_mov_b64_e32 v[38:39], v[2:3]
	v_mov_b64_e32 v[42:43], v[2:3]
	v_mov_b64_e32 v[54:55], v[2:3]
	v_mov_b64_e32 v[58:59], v[2:3]
	v_mov_b64_e32 v[14:15], v[2:3]
	v_mov_b64_e32 v[18:19], v[2:3]
	v_mov_b64_e32 v[30:31], v[2:3]
	v_mov_b64_e32 v[34:35], v[2:3]
	v_mov_b64_e32 v[46:47], v[2:3]
	v_mov_b64_e32 v[50:51], v[2:3]
	v_mov_b64_e32 v[62:63], v[2:3]
	v_mov_b64_e32 v[66:67], v[2:3]
	v_mov_b64_e32 v[70:71], v[2:3]
	v_mov_b64_e32 v[74:75], v[2:3]
	v_mov_b64_e32 v[86:87], v[2:3]
	v_mov_b64_e32 v[90:91], v[2:3]
	v_mov_b64_e32 v[102:103], v[2:3]
	v_mov_b64_e32 v[106:107], v[2:3]
	v_mov_b64_e32 v[118:119], v[2:3]
	v_mov_b64_e32 v[126:127], v[2:3]
	v_mov_b64_e32 v[78:79], v[2:3]
	v_mov_b64_e32 v[82:83], v[2:3]
	v_mov_b64_e32 v[94:95], v[2:3]
	v_mov_b64_e32 v[98:99], v[2:3]
	v_mov_b64_e32 v[110:111], v[2:3]
	v_mov_b64_e32 v[114:115], v[2:3]
	v_mov_b64_e32 v[142:143], v[2:3]
	v_mov_b64_e32 v[146:147], v[2:3]
	v_lshl_add_u64 v[138:139], s[66:67], 0, v[156:157]
	v_lshl_add_u64 v[164:165], s[66:67], 0, v[158:159]
	s_addc_u32 s75, s7, 0
	s_mov_b32 s76, -2
	s_mov_b64 s[70:71], 0
	v_mov_b64_e32 v[4:5], v[0:1]
	v_mov_b64_e32 v[8:9], v[0:1]
	v_mov_b64_e32 v[20:21], v[0:1]
	v_mov_b64_e32 v[24:25], v[0:1]
	v_mov_b64_e32 v[36:37], v[0:1]
	v_mov_b64_e32 v[40:41], v[0:1]
	v_mov_b64_e32 v[52:53], v[0:1]
	v_mov_b64_e32 v[56:57], v[0:1]
	v_mov_b64_e32 v[12:13], v[0:1]
	v_mov_b64_e32 v[16:17], v[0:1]
	v_mov_b64_e32 v[28:29], v[0:1]
	v_mov_b64_e32 v[32:33], v[0:1]
	v_mov_b64_e32 v[44:45], v[0:1]
	v_mov_b64_e32 v[48:49], v[0:1]
	v_mov_b64_e32 v[60:61], v[0:1]
	v_mov_b64_e32 v[64:65], v[0:1]
	v_mov_b64_e32 v[68:69], v[0:1]
	v_mov_b64_e32 v[72:73], v[0:1]
	v_mov_b64_e32 v[84:85], v[0:1]
	v_mov_b64_e32 v[88:89], v[0:1]
	v_mov_b64_e32 v[100:101], v[0:1]
	v_mov_b64_e32 v[104:105], v[0:1]
	v_mov_b64_e32 v[116:117], v[0:1]
	v_mov_b64_e32 v[124:125], v[0:1]
	v_mov_b64_e32 v[76:77], v[0:1]
	v_mov_b64_e32 v[80:81], v[0:1]
	v_mov_b64_e32 v[92:93], v[0:1]
	v_mov_b64_e32 v[96:97], v[0:1]
	v_mov_b64_e32 v[108:109], v[0:1]
	v_mov_b64_e32 v[112:113], v[0:1]
	v_mov_b64_e32 v[140:141], v[0:1]
	v_mov_b64_e32 v[144:145], v[0:1]
	s_branch .LBB0_899
	s_branch .Lpagefit_6
	s_nop 0
	s_nop 0
	s_nop 0
	s_nop 0
	s_nop 0
	s_nop 0
	s_nop 0
	s_nop 0
	s_nop 0
	s_nop 0
	s_nop 0
	s_nop 0
	s_nop 0
	s_nop 0
	s_nop 0
	s_nop 0
	s_nop 0
	s_nop 0
	s_nop 0
	s_nop 0
	s_nop 0
	s_nop 0
	s_nop 0
	s_nop 0
	s_nop 0
	s_nop 0
	s_nop 0
	s_nop 0
	s_nop 0
	s_nop 0
	s_nop 0
	s_nop 0
	s_nop 0
	s_nop 0
	s_nop 0
	s_nop 0
	s_nop 0
	s_nop 0
	s_nop 0
	s_nop 0
	s_nop 0
	s_nop 0
	s_nop 0
	s_nop 0
	s_nop 0
	s_nop 0
	s_nop 0
	s_nop 0
	s_nop 0
	s_nop 0
	s_nop 0
	s_nop 0
	s_nop 0
	s_nop 0
	s_nop 0
	s_nop 0
	s_nop 0
	s_nop 0
	s_nop 0
	s_nop 0
	s_nop 0
	s_nop 0
	s_nop 0
	s_nop 0
	s_nop 0
	s_nop 0
	s_nop 0
	s_nop 0
	s_nop 0
	s_nop 0
	s_nop 0
	s_nop 0
	s_nop 0
	s_nop 0
	s_nop 0
	s_nop 0
	s_nop 0
	s_nop 0
	s_nop 0
	s_nop 0
	s_nop 0
	s_nop 0
	s_nop 0
	s_nop 0
	s_nop 0
	s_nop 0
	s_nop 0
	s_nop 0
	s_nop 0
	s_nop 0
	s_nop 0
	s_nop 0
	s_nop 0
	s_nop 0
	s_nop 0
	s_nop 0
	s_nop 0
	s_nop 0
	s_nop 0
	s_nop 0
	s_nop 0
	s_nop 0
	s_nop 0
	s_nop 0
	s_nop 0
	s_nop 0
	s_nop 0
	s_nop 0
	s_nop 0
	s_nop 0
	s_nop 0
	s_nop 0
	s_nop 0
	s_nop 0
	s_nop 0
	s_nop 0
	s_nop 0
	s_nop 0
	s_nop 0
	s_nop 0
	s_nop 0
	s_nop 0
	s_nop 0
	s_nop 0
	s_nop 0
	s_nop 0
	s_nop 0
	s_nop 0
	s_nop 0
	s_nop 0
	s_nop 0
	s_nop 0
	s_nop 0
	s_nop 0
	s_nop 0
	s_nop 0
	s_nop 0
	s_nop 0
	s_nop 0
	s_nop 0
	s_nop 0
	s_nop 0
	s_nop 0
	s_nop 0
	s_nop 0
	s_nop 0
	s_nop 0
	s_nop 0
	s_nop 0
	s_nop 0
	s_nop 0
	s_nop 0
	s_nop 0
	s_nop 0
	s_nop 0
	s_nop 0
	s_nop 0
	s_nop 0
	s_nop 0
	s_nop 0
	s_nop 0
	s_nop 0
	s_nop 0
	s_nop 0
	s_nop 0
	s_nop 0
	s_nop 0
	s_nop 0
	s_nop 0
	s_nop 0
	s_nop 0
	s_nop 0
	s_nop 0
	s_nop 0
	s_nop 0
	s_nop 0
	s_nop 0
	s_nop 0
	s_nop 0
	s_nop 0
	s_nop 0
	s_nop 0
	s_nop 0
	s_nop 0
	s_nop 0
	s_nop 0
	s_nop 0
	s_nop 0
	s_nop 0
	s_nop 0
	s_nop 0
	s_nop 0
	s_nop 0
	s_nop 0
	s_nop 0
	s_nop 0
	s_nop 0
	s_nop 0
	s_nop 0
	s_nop 0
	s_nop 0
	s_nop 0
	s_nop 0
	s_nop 0
	s_nop 0
	s_nop 0
	s_nop 0
	s_nop 0
	s_nop 0
	s_nop 0
	s_nop 0
	s_nop 0
	s_nop 0
	s_nop 0
	s_nop 0
	s_nop 0
	s_nop 0
	s_nop 0
	s_nop 0
	s_nop 0
	s_nop 0
	s_nop 0
	s_nop 0
	s_nop 0
	s_nop 0
	s_nop 0
	s_nop 0
	s_nop 0
	s_nop 0
	s_nop 0
	s_nop 0
	s_nop 0
	s_nop 0
	s_nop 0
	s_nop 0
	s_nop 0
	s_nop 0
	s_nop 0
	s_nop 0
	s_nop 0
	s_nop 0
	s_nop 0
	s_nop 0
	s_nop 0
	s_nop 0
	s_nop 0
	s_nop 0
	s_nop 0
	s_nop 0
	s_nop 0
; #define PG8_STAGE(bufoff, gbase, voff) do { _Pragma("unroll") for (int _i = 0; _i < 2; ++_i) \
;         __builtin_amdgcn_global_load_lds((const unsigned*)((const char*)(gbase) + (voff)[_i]), (PG8_LAS unsigned*)(lds + (bufoff) + ldsw + _i * 8192), 16, 0, 0); } while (0)
; #define PG8_LDA(dst, b, h) do { _Pragma("unroll") for (int m = 0; m < 4; ++m) _Pragma("unroll") for (int k = 0; k < 2; ++k) dst[m][k] = *(const PG8_LAS bf16x8*)(lds + PG8_SA(b, h) + aoff + m * 2048 + k * 1024); } while (0)
; #define PG8_LDB(dst, b, h) do { _Pragma("unroll") for (int n = 0; n < 2; ++n) _Pragma("unroll") for (int k = 0; k < 2; ++k) dst[n][k] = *(const PG8_LAS bf16x8*)(lds + PG8_SB(b, h) + boff + n * 2048 + k * 1024); } while (0)
; #define PG8_MMA(ai, bj, At, Bt) do { __builtin_amdgcn_s_setprio(1); _Pragma("unroll") for (int m = 0; m < 4; ++m) _Pragma("unroll") for (int n = 0; n < 2; ++n) _Pragma("unroll") for (int k = 0; k < 2; ++k) \
;         acc[ai][bj][m][n] = __builtin_amdgcn_mfma_f32_16x16x32_bf16(Bt[n][k], At[m][k], acc[ai][bj][m][n], 0, 0, 0); __builtin_amdgcn_s_setprio(0); } while (0)
; #define PG8_WAIT_V(n) asm volatile("s_waitcnt vmcnt(" #n ")" ::: "memory")
; #define PG8_WAIT_L(n) asm volatile("s_waitcnt lgkmcnt(" #n ")" ::: "memory")
; #define PG8_BAR __builtin_amdgcn_s_barrier()
; #define PG8_SCHED __builtin_amdgcn_sched_barrier(0)
; template <class Epi, class Sched, bool ALIGN_EPI = false, bool SP2 = false>
; __device__ __forceinline__ void gemm_phase(PG8_LAS unsigned char* lds, const Gemm g, const Sched S, const Epi E) {
;     ...
;             if constexpr (SP2) {
;             PG8_LDB(B0, 0, 0); PG8_LDB(B1, 0, 1); PG8_SCHED; PG8_LDA(At, 0, 0); PG8_STAGE(PG8_SA(1, 1), a1 + hstep, voffA);
;             PG8_WAIT_V(8); PG8_WAIT_L(0); PG8_BAR; PG8_MMA(0, 0, At, B0); PG8_MMA(0, 1, At, B1); PG8_BAR; PG8_SCHED;
	s_nop 0
	s_nop 0
	s_nop 0
	s_nop 0
	s_nop 0
	s_nop 0
	s_nop 0
	s_nop 0
	s_nop 0
	s_nop 0
	s_nop 0
	s_nop 0
	s_nop 0
	s_nop 0
	s_nop 0
	s_nop 0
	s_nop 0
	s_nop 0
	s_nop 0
	s_nop 0
	s_nop 0
	s_nop 0
	s_nop 0
	s_nop 0
	s_nop 0
	s_nop 0
	s_nop 0
	s_nop 0
	s_nop 0
	s_nop 0
	s_nop 0
	s_nop 0
	s_nop 0
	s_nop 0
	s_nop 0
	s_nop 0
	s_nop 0
	s_nop 0
	s_nop 0
	s_nop 0
	s_nop 0
	s_nop 0
	s_nop 0
	s_nop 0
	s_nop 0
	s_nop 0
	s_nop 0
	s_nop 0
	s_nop 0
	s_nop 0
	s_nop 0
	s_nop 0
	s_nop 0
	s_nop 0
	s_nop 0
	s_nop 0
	s_nop 0
	s_nop 0
	s_nop 0
	s_nop 0
	s_nop 0
	s_nop 0
	s_nop 0
	s_nop 0
	s_nop 0
	s_nop 0
	s_nop 0
	s_nop 0
	s_nop 0
	s_nop 0
	s_nop 0
	s_nop 0
	s_nop 0
	s_nop 0
	s_nop 0
	s_nop 0
	s_nop 0
	s_nop 0
	s_nop 0
	s_nop 0
	s_nop 0
	s_nop 0
	s_nop 0
	s_nop 0
	s_nop 0
	s_nop 0
	s_nop 0
	s_nop 0
	s_nop 0
	s_nop 0
	s_nop 0
	s_nop 0
	s_nop 0
	s_nop 0
	s_nop 0
	s_nop 0
	s_nop 0
	s_nop 0
	s_nop 0
	s_nop 0
	s_nop 0
	s_nop 0
	s_nop 0
	s_nop 0
	s_nop 0
	s_nop 0
	s_nop 0
	s_nop 0
	s_nop 0
	s_nop 0
	s_nop 0
	s_nop 0
	s_nop 0
	s_nop 0
	s_nop 0
	s_nop 0
	s_nop 0
	s_nop 0
	s_nop 0
	s_nop 0
	s_nop 0
	s_nop 0
	s_nop 0
	s_nop 0
	s_nop 0
	s_nop 0
	s_nop 0
	s_nop 0
	s_nop 0
	s_nop 0
	s_nop 0
	s_nop 0
	s_nop 0
	s_nop 0
	s_nop 0
	s_nop 0
	s_nop 0
	s_nop 0
	s_nop 0
	s_nop 0
	s_nop 0
	s_nop 0
	s_nop 0
	s_nop 0
	s_nop 0
	s_nop 0
	s_nop 0
	s_nop 0
	s_nop 0
	s_nop 0
	s_nop 0
	s_nop 0
	s_nop 0
	s_nop 0
	s_nop 0
	s_nop 0
	s_nop 0
	s_nop 0
	s_nop 0
	s_nop 0
	s_nop 0
	s_nop 0
	s_nop 0
	s_nop 0
	s_nop 0
	s_nop 0
	s_nop 0
	s_nop 0
	s_nop 0
	s_nop 0
	s_nop 0
	s_nop 0
	s_nop 0
	s_nop 0
	s_nop 0
	s_nop 0
	s_nop 0
	s_nop 0
	s_nop 0
	s_nop 0
	s_nop 0
	s_nop 0
	s_nop 0
	s_nop 0
	s_nop 0
	s_nop 0
	s_nop 0
	s_nop 0
	s_nop 0
	s_nop 0
	s_nop 0
	s_nop 0
	s_nop 0
	s_nop 0
	s_nop 0
	s_nop 0
	s_nop 0
	s_nop 0
	s_nop 0
	s_nop 0
	s_nop 0
	s_nop 0
	s_nop 0
	s_nop 0
	s_nop 0
	s_nop 0
	s_nop 0
	s_nop 0
	s_nop 0
	s_nop 0
	s_nop 0
	s_nop 0
	s_nop 0
	s_nop 0
	s_nop 0
	s_nop 0
	s_nop 0
	s_nop 0
	s_nop 0
	s_nop 0
	s_nop 0
	s_nop 0
	s_nop 0
	s_nop 0
	s_nop 0
	s_nop 0
	s_nop 0
	s_nop 0
	s_nop 0
	s_nop 0
	s_nop 0
	s_nop 0
	s_nop 0
	s_nop 0
	s_nop 0
	s_nop 0
	s_nop 0
	s_nop 0
	s_nop 0
	s_nop 0
	s_nop 0
	s_nop 0
	s_nop 0
	s_nop 0
	s_nop 0
	s_nop 0
	s_nop 0
	s_nop 0
	s_nop 0
	s_nop 0
	s_nop 0
	s_nop 0
	s_nop 0
	s_nop 0
	s_nop 0
	s_nop 0
	s_nop 0
	s_nop 0
	s_nop 0
	s_nop 0
	s_nop 0
	s_nop 0
	s_nop 0
	s_nop 0
	s_nop 0
	s_nop 0
	s_nop 0
	s_nop 0
	s_nop 0
	s_nop 0
	s_nop 0
	s_nop 0
	s_nop 0
	s_nop 0
	s_nop 0
	s_nop 0
	s_nop 0
	s_nop 0
	s_nop 0
	s_nop 0
	s_nop 0
	s_nop 0
	s_nop 0
	s_nop 0
	s_nop 0
	s_nop 0
	s_nop 0
	s_nop 0
	s_nop 0
	s_nop 0
	s_nop 0
	s_nop 0
	s_nop 0
	s_nop 0
	s_nop 0
	s_nop 0
	s_nop 0
	s_nop 0
	s_nop 0
	s_nop 0
	s_nop 0
	s_nop 0
.Lpagefit_6:
.LBB0_898:
	v_add_u32_e32 v1, s65, v170
	ds_read_b128 v[120:123], v1
	ds_read_b128 v[176:179], v1 offset:1024
	ds_read_b128 v[180:183], v1 offset:2048
	ds_read_b128 v[190:193], v1 offset:3072
	v_add_u32_e32 v1, s68, v170
	s_add_u32 s6, s66, s70
	ds_read_b128 v[194:197], v1
	ds_read_b128 v[198:201], v1 offset:1024
	ds_read_b128 v[202:205], v1 offset:2048
	ds_read_b128 v[206:209], v1 offset:3072
	s_addc_u32 s7, s67, s71
	s_add_u32 s6, s6, 0x100
	s_addc_u32 s7, s7, 0
	s_add_u32 s14, s74, s70
	s_addc_u32 s15, s75, s71
	s_cmpk_eq_i32 s70, 0x700
	s_cselect_b32 s11, s51, s7
	s_cselect_b32 s10, s72, s6
	s_cselect_b32 s7, s45, s15
	s_cselect_b32 s6, s73, s14
	v_lshl_add_u64 v[2:3], v[138:139], 0, s[70:71]
	s_add_i32 m0, s9, 0xc000
	ds_read_b128 v[210:213], v173
	ds_read_b128 v[214:217], v173 offset:1024
	ds_read_b128 v[218:221], v173 offset:2048
	ds_read_b128 v[222:225], v173 offset:3072
	ds_read_b128 v[226:229], v173 offset:4096
	ds_read_b128 v[230:233], v173 offset:5120
	ds_read_b128 v[234:237], v173 offset:6144
	ds_read_b128 v[238:241], v173 offset:7168
	global_load_lds_dwordx4 v[2:3], off
	v_lshl_add_u64 v[2:3], v[164:165], 0, s[70:71]
	s_add_i32 m0, s9, 0xe000
	s_nop 0
	global_load_lds_dwordx4 v[2:3], off
	s_waitcnt vmcnt(8)
	s_waitcnt lgkmcnt(0)
	s_barrier
	s_setprio 1
	s_waitcnt lgkmcnt(0)
	v_mfma_f32_16x16x32_bf16 v[144:147], v[120:123], v[210:213], v[144:147]
	v_mfma_f32_16x16x32_bf16 v[140:143], v[180:183], v[210:213], v[140:143]
	v_mfma_f32_16x16x32_bf16 v[112:115], v[120:123], v[218:221], v[112:115]
	v_mfma_f32_16x16x32_bf16 v[108:111], v[180:183], v[218:221], v[108:111]
	v_mfma_f32_16x16x32_bf16 v[96:99], v[120:123], v[226:229], v[96:99]
	v_mfma_f32_16x16x32_bf16 v[92:95], v[180:183], v[226:229], v[92:95]
	v_mfma_f32_16x16x32_bf16 v[80:83], v[120:123], v[234:237], v[80:83]
	v_mfma_f32_16x16x32_bf16 v[76:79], v[180:183], v[234:237], v[76:79]
	v_mfma_f32_16x16x32_bf16 v[144:147], v[176:179], v[214:217], v[144:147]
	v_mfma_f32_16x16x32_bf16 v[140:143], v[190:193], v[214:217], v[140:143]
	v_mfma_f32_16x16x32_bf16 v[112:115], v[176:179], v[222:225], v[112:115]
	v_mfma_f32_16x16x32_bf16 v[108:111], v[190:193], v[222:225], v[108:111]
	v_mfma_f32_16x16x32_bf16 v[96:99], v[176:179], v[230:233], v[96:99]
	v_mfma_f32_16x16x32_bf16 v[92:95], v[190:193], v[230:233], v[92:95]
	v_mfma_f32_16x16x32_bf16 v[80:83], v[176:179], v[238:241], v[80:83]
	v_mfma_f32_16x16x32_bf16 v[76:79], v[190:193], v[238:241], v[76:79]
	s_setprio 0
	s_setprio 1
	v_mfma_f32_16x16x32_bf16 v[124:127], v[194:197], v[210:213], v[124:127]
	v_mfma_f32_16x16x32_bf16 v[116:119], v[202:205], v[210:213], v[116:119]
	v_mfma_f32_16x16x32_bf16 v[104:107], v[194:197], v[218:221], v[104:107]
	v_mfma_f32_16x16x32_bf16 v[100:103], v[202:205], v[218:221], v[100:103]
	v_mfma_f32_16x16x32_bf16 v[88:91], v[194:197], v[226:229], v[88:91]
	v_mfma_f32_16x16x32_bf16 v[84:87], v[202:205], v[226:229], v[84:87]
	v_mfma_f32_16x16x32_bf16 v[72:75], v[194:197], v[234:237], v[72:75]
	v_mfma_f32_16x16x32_bf16 v[68:71], v[202:205], v[234:237], v[68:71]
	v_mfma_f32_16x16x32_bf16 v[124:127], v[198:201], v[214:217], v[124:127]
	v_mfma_f32_16x16x32_bf16 v[116:119], v[206:209], v[214:217], v[116:119]
	v_mfma_f32_16x16x32_bf16 v[104:107], v[198:201], v[222:225], v[104:107]
	v_mfma_f32_16x16x32_bf16 v[100:103], v[206:209], v[222:225], v[100:103]
	v_mfma_f32_16x16x32_bf16 v[88:91], v[198:201], v[230:233], v[88:91]
	v_mfma_f32_16x16x32_bf16 v[84:87], v[206:209], v[230:233], v[84:87]
	v_mfma_f32_16x16x32_bf16 v[72:75], v[198:201], v[238:241], v[72:75]
	v_mfma_f32_16x16x32_bf16 v[68:71], v[206:209], v[238:241], v[68:71]
	s_setprio 0
	s_barrier
; #define PG8_STAGE(bufoff, gbase, voff) do { _Pragma("unroll") for (int _i = 0; _i < 2; ++_i) \
;         __builtin_amdgcn_global_load_lds((const unsigned*)((const char*)(gbase) + (voff)[_i]), (PG8_LAS unsigned*)(lds + (bufoff) + ldsw + _i * 8192), 16, 0, 0); } while (0)
; #define PG8_LDA(dst, b, h) do { _Pragma("unroll") for (int m = 0; m < 4; ++m) _Pragma("unroll") for (int k = 0; k < 2; ++k) dst[m][k] = *(const PG8_LAS bf16x8*)(lds + PG8_SA(b, h) + aoff + m * 2048 + k * 1024); } while (0)
; #define PG8_LDB(dst, b, h) do { _Pragma("unroll") for (int n = 0; n < 2; ++n) _Pragma("unroll") for (int k = 0; k < 2; ++k) dst[n][k] = *(const PG8_LAS bf16x8*)(lds + PG8_SB(b, h) + boff + n * 2048 + k * 1024); } while (0)
; #define PG8_MMA(ai, bj, At, Bt) do { __builtin_amdgcn_s_setprio(1); _Pragma("unroll") for (int m = 0; m < 4; ++m) _Pragma("unroll") for (int n = 0; n < 2; ++n) _Pragma("unroll") for (int k = 0; k < 2; ++k) \
;         acc[ai][bj][m][n] = __builtin_amdgcn_mfma_f32_16x16x32_bf16(Bt[n][k], At[m][k], acc[ai][bj][m][n], 0, 0, 0); __builtin_amdgcn_s_setprio(0); } while (0)
; #define PG8_WAIT_V(n) asm volatile("s_waitcnt vmcnt(" #n ")" ::: "memory")
; #define PG8_WAIT_L(n) asm volatile("s_waitcnt lgkmcnt(" #n ")" ::: "memory")
; #define PG8_BAR __builtin_amdgcn_s_barrier()
; #define PG8_SCHED __builtin_amdgcn_sched_barrier(0)
; template <class Epi, class Sched, bool ALIGN_EPI = false, bool SP2 = false>
; __device__ __forceinline__ void gemm_phase(PG8_LAS unsigned char* lds, const Gemm g, const Sched S, const Epi E) {
;     ...
;             PG8_LDA(At, 0, 1); PG8_STAGE(PG8_SB(0, 0), b2, voffB); PG8_STAGE(PG8_SB(0, 1), b2 + hstep, voffB); PG8_STAGE(PG8_SA(0, 0), a2, voffA);
;             PG8_WAIT_V(8); PG8_WAIT_L(0); PG8_BAR; PG8_MMA(1, 0, At, B0); PG8_MMA(1, 1, At, B1); PG8_BAR; PG8_SCHED;
;             PG8_LDB(B0, 1, 0); PG8_LDB(B1, 1, 1); PG8_SCHED; PG8_LDA(At, 1, 0); PG8_STAGE(PG8_SA(0, 1), a2 + hstep, voffA);
;             PG8_WAIT_V(8); PG8_WAIT_L(0); PG8_BAR; PG8_MMA(0, 0, At, B0); PG8_MMA(0, 1, At, B1); PG8_BAR; PG8_SCHED;
	s_add_i32 s14, s65, s8
	v_lshl_add_u64 v[166:167], s[6:7], 0, v[150:151]
	s_mov_b32 m0, s14
	ds_read_b128 v[210:213], v173 offset:16384
	ds_read_b128 v[214:217], v173 offset:17408
	ds_read_b128 v[218:221], v173 offset:18432
	ds_read_b128 v[222:225], v173 offset:19456
	ds_read_b128 v[226:229], v173 offset:20480
	ds_read_b128 v[230:233], v173 offset:21504
	ds_read_b128 v[234:237], v173 offset:22528
	ds_read_b128 v[238:241], v173 offset:23552
	global_load_lds_dwordx4 v[166:167], off
	s_add_i32 m0, s14, 0x2000
	s_add_u32 s14, s6, 0x40000
	v_lshl_add_u64 v[184:185], s[6:7], 0, v[154:155]
	s_addc_u32 s15, s7, 0
	s_add_i32 s77, s68, s8
	global_load_lds_dwordx4 v[184:185], off
	v_lshl_add_u64 v[2:3], s[14:15], 0, v[150:151]
	s_mov_b32 m0, s77
	v_lshl_add_u64 v[186:187], s[10:11], 0, v[148:149]
	global_load_lds_dwordx4 v[2:3], off
	v_lshl_add_u64 v[2:3], s[14:15], 0, v[154:155]
	s_add_i32 m0, s77, 0x2000
	v_lshl_add_u64 v[242:243], s[10:11], 0, v[152:153]
	global_load_lds_dwordx4 v[2:3], off
	s_mov_b32 m0, s9
	s_nop 0
	global_load_lds_dwordx4 v[186:187], off
	s_mov_b32 m0, s12
	s_nop 0
	global_load_lds_dwordx4 v[242:243], off
	s_waitcnt vmcnt(8)
	s_waitcnt lgkmcnt(0)
	s_barrier
	s_setprio 1
	s_waitcnt lgkmcnt(0)
	v_mfma_f32_16x16x32_bf16 v[64:67], v[120:123], v[210:213], v[64:67]
	v_mfma_f32_16x16x32_bf16 v[60:63], v[180:183], v[210:213], v[60:63]
	v_mfma_f32_16x16x32_bf16 v[48:51], v[120:123], v[218:221], v[48:51]
	v_mfma_f32_16x16x32_bf16 v[44:47], v[180:183], v[218:221], v[44:47]
	v_mfma_f32_16x16x32_bf16 v[32:35], v[120:123], v[226:229], v[32:35]
	v_mfma_f32_16x16x32_bf16 v[28:31], v[180:183], v[226:229], v[28:31]
	v_mfma_f32_16x16x32_bf16 v[16:19], v[120:123], v[234:237], v[16:19]
	v_mfma_f32_16x16x32_bf16 v[12:15], v[180:183], v[234:237], v[12:15]
	v_mfma_f32_16x16x32_bf16 v[64:67], v[176:179], v[214:217], v[64:67]
	v_mfma_f32_16x16x32_bf16 v[60:63], v[190:193], v[214:217], v[60:63]
	v_mfma_f32_16x16x32_bf16 v[48:51], v[176:179], v[222:225], v[48:51]
	v_mfma_f32_16x16x32_bf16 v[44:47], v[190:193], v[222:225], v[44:47]
	v_mfma_f32_16x16x32_bf16 v[32:35], v[176:179], v[230:233], v[32:35]
	v_mfma_f32_16x16x32_bf16 v[28:31], v[190:193], v[230:233], v[28:31]
	v_mfma_f32_16x16x32_bf16 v[16:19], v[176:179], v[238:241], v[16:19]
	v_mfma_f32_16x16x32_bf16 v[12:15], v[190:193], v[238:241], v[12:15]
	s_setprio 0
	s_setprio 1
	v_mfma_f32_16x16x32_bf16 v[56:59], v[194:197], v[210:213], v[56:59]
	v_mfma_f32_16x16x32_bf16 v[52:55], v[202:205], v[210:213], v[52:55]
	v_mfma_f32_16x16x32_bf16 v[40:43], v[194:197], v[218:221], v[40:43]
	v_mfma_f32_16x16x32_bf16 v[36:39], v[202:205], v[218:221], v[36:39]
	v_mfma_f32_16x16x32_bf16 v[24:27], v[194:197], v[226:229], v[24:27]
	v_mfma_f32_16x16x32_bf16 v[20:23], v[202:205], v[226:229], v[20:23]
	v_mfma_f32_16x16x32_bf16 v[8:11], v[194:197], v[234:237], v[8:11]
	v_mfma_f32_16x16x32_bf16 v[2:5], v[202:205], v[234:237], v[4:7]
	v_mfma_f32_16x16x32_bf16 v[56:59], v[198:201], v[214:217], v[56:59]
	v_mfma_f32_16x16x32_bf16 v[52:55], v[206:209], v[214:217], v[52:55]
	v_mfma_f32_16x16x32_bf16 v[40:43], v[198:201], v[222:225], v[40:43]
	v_mfma_f32_16x16x32_bf16 v[36:39], v[206:209], v[222:225], v[36:39]
	v_mfma_f32_16x16x32_bf16 v[24:27], v[198:201], v[230:233], v[24:27]
	v_mfma_f32_16x16x32_bf16 v[20:23], v[206:209], v[230:233], v[20:23]
	v_mfma_f32_16x16x32_bf16 v[8:11], v[198:201], v[238:241], v[8:11]
	v_mfma_f32_16x16x32_bf16 v[2:5], v[206:209], v[238:241], v[2:5]
	s_setprio 0
	s_barrier
	s_add_i32 s14, 0, 0x18000
	v_add_u32_e32 v1, s14, v170
	s_add_i32 s15, 0, 0x1c000
	ds_read_b128 v[120:123], v1
	ds_read_b128 v[176:179], v1 offset:1024
	ds_read_b128 v[180:183], v1 offset:2048
	ds_read_b128 v[190:193], v1 offset:3072
	v_add_u32_e32 v1, s15, v170
	ds_read_b128 v[194:197], v1
	ds_read_b128 v[198:201], v1 offset:1024
	ds_read_b128 v[202:205], v1 offset:2048
	ds_read_b128 v[206:209], v1 offset:3072
	s_add_u32 s10, s10, 0x40000
	s_addc_u32 s11, s11, 0
	s_mov_b32 m0, s13
	v_lshl_add_u64 v[6:7], s[10:11], 0, v[148:149]
	ds_read_b128 v[210:213], v173 offset:32768
	ds_read_b128 v[214:217], v173 offset:33792
	ds_read_b128 v[218:221], v173 offset:34816
	ds_read_b128 v[222:225], v173 offset:35840
	ds_read_b128 v[226:229], v173 offset:36864
	ds_read_b128 v[230:233], v173 offset:37888
	ds_read_b128 v[234:237], v173 offset:38912
	ds_read_b128 v[238:241], v173 offset:39936
	global_load_lds_dwordx4 v[6:7], off
	v_lshl_add_u64 v[6:7], s[10:11], 0, v[152:153]
	s_mov_b32 m0, s33
	s_nop 0
	global_load_lds_dwordx4 v[6:7], off
	s_waitcnt vmcnt(8)
	s_waitcnt lgkmcnt(0)
	s_barrier
; #define PG8_STAGE(bufoff, gbase, voff) do { _Pragma("unroll") for (int _i = 0; _i < 2; ++_i) \
;         __builtin_amdgcn_global_load_lds((const unsigned*)((const char*)(gbase) + (voff)[_i]), (PG8_LAS unsigned*)(lds + (bufoff) + ldsw + _i * 8192), 16, 0, 0); } while (0)
; #define PG8_LDA(dst, b, h) do { _Pragma("unroll") for (int m = 0; m < 4; ++m) _Pragma("unroll") for (int k = 0; k < 2; ++k) dst[m][k] = *(const PG8_LAS bf16x8*)(lds + PG8_SA(b, h) + aoff + m * 2048 + k * 1024); } while (0)
; #define PG8_MMA(ai, bj, At, Bt) do { __builtin_amdgcn_s_setprio(1); _Pragma("unroll") for (int m = 0; m < 4; ++m) _Pragma("unroll") for (int n = 0; n < 2; ++n) _Pragma("unroll") for (int k = 0; k < 2; ++k) \
;         acc[ai][bj][m][n] = __builtin_amdgcn_mfma_f32_16x16x32_bf16(Bt[n][k], At[m][k], acc[ai][bj][m][n], 0, 0, 0); __builtin_amdgcn_s_setprio(0); } while (0)
; #define PG8_WAIT_V(n) asm volatile("s_waitcnt vmcnt(" #n ")" ::: "memory")
; #define PG8_WAIT_L(n) asm volatile("s_waitcnt lgkmcnt(" #n ")" ::: "memory")
; #define PG8_BAR __builtin_amdgcn_s_barrier()
; #define PG8_SCHED __builtin_amdgcn_sched_barrier(0)
; template <class Epi, class Sched, bool ALIGN_EPI = false, bool SP2 = false>
; __device__ __forceinline__ void gemm_phase(PG8_LAS unsigned char* lds, const Gemm g, const Sched S, const Epi E) {
;     ...
;         for (int t = 0; t < nt; t += 2) {
;     ...
;             PG8_WAIT_V(8); PG8_WAIT_L(0); PG8_BAR; PG8_MMA(0, 0, At, B0); PG8_MMA(0, 1, At, B1); PG8_BAR; PG8_SCHED;
;             PG8_LDA(At, 1, 1); PG8_STAGE(PG8_SB(1, 0), b3, voffB); PG8_STAGE(PG8_SB(1, 1), b3 + hstep, voffB); PG8_STAGE(PG8_SA(1, 0), a3, voffA);
;             PG8_WAIT_V(8); PG8_WAIT_L(0); PG8_BAR; PG8_MMA(1, 0, At, B0); PG8_MMA(1, 1, At, B1); PG8_BAR; PG8_SCHED;
	s_setprio 1
	s_waitcnt lgkmcnt(0)
	v_mfma_f32_16x16x32_bf16 v[144:147], v[120:123], v[210:213], v[144:147]
	v_mfma_f32_16x16x32_bf16 v[140:143], v[180:183], v[210:213], v[140:143]
	v_mfma_f32_16x16x32_bf16 v[112:115], v[120:123], v[218:221], v[112:115]
	v_mfma_f32_16x16x32_bf16 v[108:111], v[180:183], v[218:221], v[108:111]
	v_mfma_f32_16x16x32_bf16 v[96:99], v[120:123], v[226:229], v[96:99]
	v_mfma_f32_16x16x32_bf16 v[92:95], v[180:183], v[226:229], v[92:95]
	v_mfma_f32_16x16x32_bf16 v[80:83], v[120:123], v[234:237], v[80:83]
	v_mfma_f32_16x16x32_bf16 v[76:79], v[180:183], v[234:237], v[76:79]
	v_mfma_f32_16x16x32_bf16 v[144:147], v[176:179], v[214:217], v[144:147]
	v_mfma_f32_16x16x32_bf16 v[140:143], v[190:193], v[214:217], v[140:143]
	v_mfma_f32_16x16x32_bf16 v[112:115], v[176:179], v[222:225], v[112:115]
	v_mfma_f32_16x16x32_bf16 v[108:111], v[190:193], v[222:225], v[108:111]
	v_mfma_f32_16x16x32_bf16 v[96:99], v[176:179], v[230:233], v[96:99]
	v_mfma_f32_16x16x32_bf16 v[92:95], v[190:193], v[230:233], v[92:95]
	v_mfma_f32_16x16x32_bf16 v[80:83], v[176:179], v[238:241], v[80:83]
	v_mfma_f32_16x16x32_bf16 v[76:79], v[190:193], v[238:241], v[76:79]
	s_setprio 0
	s_setprio 1
	v_mfma_f32_16x16x32_bf16 v[124:127], v[194:197], v[210:213], v[124:127]
	v_mfma_f32_16x16x32_bf16 v[116:119], v[202:205], v[210:213], v[116:119]
	v_mfma_f32_16x16x32_bf16 v[104:107], v[194:197], v[218:221], v[104:107]
	v_mfma_f32_16x16x32_bf16 v[100:103], v[202:205], v[218:221], v[100:103]
	v_mfma_f32_16x16x32_bf16 v[88:91], v[194:197], v[226:229], v[88:91]
	v_mfma_f32_16x16x32_bf16 v[84:87], v[202:205], v[226:229], v[84:87]
	v_mfma_f32_16x16x32_bf16 v[72:75], v[194:197], v[234:237], v[72:75]
	v_mfma_f32_16x16x32_bf16 v[68:71], v[202:205], v[234:237], v[68:71]
	v_mfma_f32_16x16x32_bf16 v[124:127], v[198:201], v[214:217], v[124:127]
	v_mfma_f32_16x16x32_bf16 v[116:119], v[206:209], v[214:217], v[116:119]
	v_mfma_f32_16x16x32_bf16 v[104:107], v[198:201], v[222:225], v[104:107]
	v_mfma_f32_16x16x32_bf16 v[100:103], v[206:209], v[222:225], v[100:103]
	v_mfma_f32_16x16x32_bf16 v[88:91], v[198:201], v[230:233], v[88:91]
	v_mfma_f32_16x16x32_bf16 v[84:87], v[206:209], v[230:233], v[84:87]
	v_mfma_f32_16x16x32_bf16 v[72:75], v[198:201], v[238:241], v[72:75]
	v_mfma_f32_16x16x32_bf16 v[68:71], v[206:209], v[238:241], v[68:71]
	s_setprio 0
	s_barrier
	s_add_i32 s10, s14, s8
	v_lshl_add_u64 v[6:7], v[166:167], 0, s[18:19]
	s_mov_b32 m0, s10
	ds_read_b128 v[210:213], v173 offset:49152
	ds_read_b128 v[214:217], v173 offset:50176
	ds_read_b128 v[218:221], v173 offset:51200
	ds_read_b128 v[222:225], v173 offset:52224
	ds_read_b128 v[226:229], v173 offset:53248
	ds_read_b128 v[230:233], v173 offset:54272
	ds_read_b128 v[234:237], v173 offset:55296
	ds_read_b128 v[238:241], v173 offset:56320
	global_load_lds_dwordx4 v[6:7], off
	s_add_i32 m0, s10, 0x2000
	s_add_u32 s6, s6, 0x40080
	v_lshl_add_u64 v[6:7], v[184:185], 0, s[18:19]
	s_addc_u32 s7, s7, 0
	s_add_i32 s10, s15, s8
	global_load_lds_dwordx4 v[6:7], off
	v_lshl_add_u64 v[6:7], s[6:7], 0, v[150:151]
	s_mov_b32 m0, s10
	s_nop 0
	global_load_lds_dwordx4 v[6:7], off
	v_lshl_add_u64 v[6:7], s[6:7], 0, v[154:155]
	s_add_i32 m0, s10, 0x2000
	s_nop 0
	global_load_lds_dwordx4 v[6:7], off
	v_lshl_add_u64 v[6:7], v[186:187], 0, s[18:19]
	s_mov_b32 m0, s55
	s_nop 0
	global_load_lds_dwordx4 v[6:7], off
	v_lshl_add_u64 v[6:7], v[242:243], 0, s[18:19]
	s_mov_b32 m0, s58
	s_nop 0
	global_load_lds_dwordx4 v[6:7], off
	s_waitcnt vmcnt(8)
	s_waitcnt lgkmcnt(0)
	s_barrier
	s_setprio 1
	s_waitcnt lgkmcnt(0)
	v_mfma_f32_16x16x32_bf16 v[64:67], v[120:123], v[210:213], v[64:67]
	v_mfma_f32_16x16x32_bf16 v[60:63], v[180:183], v[210:213], v[60:63]
	v_mfma_f32_16x16x32_bf16 v[48:51], v[120:123], v[218:221], v[48:51]
	v_mfma_f32_16x16x32_bf16 v[44:47], v[180:183], v[218:221], v[44:47]
	v_mfma_f32_16x16x32_bf16 v[32:35], v[120:123], v[226:229], v[32:35]
	v_mfma_f32_16x16x32_bf16 v[28:31], v[180:183], v[226:229], v[28:31]
	v_mfma_f32_16x16x32_bf16 v[16:19], v[120:123], v[234:237], v[16:19]
	v_mfma_f32_16x16x32_bf16 v[12:15], v[180:183], v[234:237], v[12:15]
	v_mfma_f32_16x16x32_bf16 v[64:67], v[176:179], v[214:217], v[64:67]
	v_mfma_f32_16x16x32_bf16 v[60:63], v[190:193], v[214:217], v[60:63]
	v_mfma_f32_16x16x32_bf16 v[48:51], v[176:179], v[222:225], v[48:51]
	v_mfma_f32_16x16x32_bf16 v[44:47], v[190:193], v[222:225], v[44:47]
	v_mfma_f32_16x16x32_bf16 v[32:35], v[176:179], v[230:233], v[32:35]
	v_mfma_f32_16x16x32_bf16 v[28:31], v[190:193], v[230:233], v[28:31]
	v_mfma_f32_16x16x32_bf16 v[16:19], v[176:179], v[238:241], v[16:19]
	v_mfma_f32_16x16x32_bf16 v[12:15], v[190:193], v[238:241], v[12:15]
	s_setprio 0
	s_setprio 1
	v_mfma_f32_16x16x32_bf16 v[56:59], v[194:197], v[210:213], v[56:59]
	v_mfma_f32_16x16x32_bf16 v[52:55], v[202:205], v[210:213], v[52:55]
	v_mfma_f32_16x16x32_bf16 v[40:43], v[194:197], v[218:221], v[40:43]
	v_mfma_f32_16x16x32_bf16 v[36:39], v[202:205], v[218:221], v[36:39]
	v_mfma_f32_16x16x32_bf16 v[24:27], v[194:197], v[226:229], v[24:27]
	v_mfma_f32_16x16x32_bf16 v[20:23], v[202:205], v[226:229], v[20:23]
	v_mfma_f32_16x16x32_bf16 v[6:9], v[194:197], v[234:237], v[8:11]
	v_mfma_f32_16x16x32_bf16 v[2:5], v[202:205], v[234:237], v[2:5]
	v_mfma_f32_16x16x32_bf16 v[56:59], v[198:201], v[214:217], v[56:59]
	v_mfma_f32_16x16x32_bf16 v[52:55], v[206:209], v[214:217], v[52:55]
	v_mfma_f32_16x16x32_bf16 v[40:43], v[198:201], v[222:225], v[40:43]
	v_mfma_f32_16x16x32_bf16 v[36:39], v[206:209], v[222:225], v[36:39]
	v_mfma_f32_16x16x32_bf16 v[24:27], v[198:201], v[230:233], v[24:27]
	v_mfma_f32_16x16x32_bf16 v[20:23], v[206:209], v[230:233], v[20:23]
	v_mfma_f32_16x16x32_bf16 v[8:11], v[198:201], v[238:241], v[6:9]
	v_mfma_f32_16x16x32_bf16 v[4:7], v[206:209], v[238:241], v[2:5]
	s_setprio 0
	s_barrier
	s_add_i32 s76, s76, 2
	s_add_u32 s70, s70, 0x100
	s_addc_u32 s71, s71, 0
	s_cmp_gt_u32 s76, 13
	s_cbranch_scc1 .LBB0_901
